# ssd-chunk-loop flat-to-global loads + counted vmcnt(8) after BC prefetch
# speedup vs baseline: 1.0007x; 1.0007x over previous
; __device__ __forceinline__ unsigned cvt_pk_bf16(float lo, float hi) { unsigned r; asm volatile("v_cvt_pk_bf16_f32 %0, %1, %2" : "=v"(r) : "v"(lo), "v"(hi)); return r; }
; __device__ __forceinline__ float bflo(unsigned u) { return __uint_as_float(u << 16); }
; template <int VAR, bool SIDE> ...
;     ...
;         f32x4 o2[2][2];
;         { const f32x4 ba = *(const LAS f32x4*)(cwt + 256 + xch * 8), bb = *(const LAS f32x4*)(cwt + 256 + xch * 8 + 4); o2[0][0] = ba; o2[0][1] = bb; o2[1][0] = ba; o2[1][1] = bb; }
; #pragma unroll
;         for (int j = 0; j < 4; ++j) { const f32x4 wa = *(const LAS f32x4*)(cwt + j * 64 + xch * 8), wb = *(const LAS f32x4*)(cwt + j * 64 + xch * 8 + 4);
; #pragma unroll
;             for (int rr = 0; rr < 2; ++rr) { const u32x4 rv = xraw[rr + j];
;                 o2[rr][0] += (f32x4){bflo(rv.x), bfhi(rv.x), bflo(rv.y), bfhi(rv.y)} * wa; o2[rr][1] += (f32x4){bflo(rv.z), bfhi(rv.z), bflo(rv.w), bfhi(rv.w)} * wb; } }
;         { f32x4 t[2][2];
; #pragma unroll
;             for (int rr = 0; rr < 2; ++rr)
; #pragma unroll
;                 for (int hq = 0; hq < 2; ++hq)
;                     { const f32x4 ta = o2[rr][hq] * -1.4426950408889634f;
; #pragma unroll
;                       for (int e = 0; e < 4; ++e) t[rr][hq][e] = __builtin_amdgcn_exp2f(ta[e]); }
; #pragma unroll
;             for (int rr = 0; rr < 2; ++rr)
; #pragma unroll
;                 for (int hq = 0; hq < 2; ++hq)
;                     { const f32x4 tb = t[rr][hq] + 1.0f;
; #pragma unroll
;                       for (int e = 0; e < 4; ++e) t[rr][hq][e] = __builtin_amdgcn_rcpf(tb[e]); }
; #pragma unroll
;             for (int rr = 0; rr < 2; ++rr)
; #pragma unroll
;                 for (int hq = 0; hq < 2; ++hq) o2[rr][hq] = o2[rr][hq] * t[rr][hq]; }
; #pragma unroll
;         for (int rr = 0; rr < 2; ++rr) { const f32x4 oa = o2[rr][0], ob = o2[rr][1];
;             u32x4 w; w.x = cvt_pk_bf16(oa[0], oa[1]); w.y = cvt_pk_bf16(oa[2], oa[3]); w.z = cvt_pk_bf16(ob[0], ob[1]); w.w = cvt_pk_bf16(ob[2], ob[3]);
;             *(LAS u32x4*)(Xs + (xr0 + rr) * XS + xch * 16) = w;
;             const float f = wl[xr0 + rr]; const f32x4 pa = oa * f, pb = ob * f;
;             w.x = cvt_pk_bf16(pa[0], pa[1]); w.y = cvt_pk_bf16(pa[2], pa[3]); w.z = cvt_pk_bf16(pb[0], pb[1]); w.w = cvt_pk_bf16(pb[2], pb[3]);
;             *(LAS u32x4*)(Xw + (xr0 + rr) * XS + xch * 16) = w; }
.LBB0_411:
	ds_read_b128 v[72:75], v221
	ds_read_b128 v[76:79], v221 offset:16
	ds_read_b128 v[80:83], v222
	ds_read_b128 v[84:87], v222 offset:16
	v_lshlrev_b32_e32 v88, 16, v8
	v_and_b32_e32 v89, 0xffff0000, v8
	v_lshlrev_b32_e32 v90, 16, v9
	v_and_b32_e32 v91, 0xffff0000, v9
	v_lshlrev_b32_e32 v92, 16, v10
	v_and_b32_e32 v93, 0xffff0000, v10
	v_lshlrev_b32_e32 v94, 16, v11
	v_and_b32_e32 v95, 0xffff0000, v11
	v_lshlrev_b32_e32 v96, 16, v4
	v_and_b32_e32 v97, 0xffff0000, v4
	v_lshlrev_b32_e32 v98, 16, v5
	v_and_b32_e32 v99, 0xffff0000, v5
	v_lshlrev_b32_e32 v100, 16, v6
	v_and_b32_e32 v101, 0xffff0000, v6
	v_lshlrev_b32_e32 v102, 16, v7
	v_and_b32_e32 v103, 0xffff0000, v7
	s_waitcnt lgkmcnt(0)
	v_pk_fma_f32 v[88:89], v[80:81], v[88:89], v[72:73]
	v_pk_fma_f32 v[90:91], v[82:83], v[90:91], v[74:75]
	v_pk_fma_f32 v[92:93], v[84:85], v[92:93], v[76:77]
	v_pk_fma_f32 v[94:95], v[86:87], v[94:95], v[78:79]
	v_pk_fma_f32 v[80:81], v[80:81], v[96:97], v[72:73]
	v_pk_fma_f32 v[82:83], v[82:83], v[98:99], v[74:75]
	v_pk_fma_f32 v[84:85], v[84:85], v[100:101], v[76:77]
	v_pk_fma_f32 v[86:87], v[86:87], v[102:103], v[78:79]
	ds_read_b128 v[72:75], v222 offset:256
	ds_read_b128 v[76:79], v222 offset:272
	s_and_b32 s94, s95, 0x80
	s_lshl_b32 s46, s94, 2
	s_add_i32 s33, s46, 0
	s_waitcnt lgkmcnt(0)
	v_pk_fma_f32 v[90:91], v[74:75], v[98:99], v[90:91]
	v_pk_fma_f32 v[88:89], v[72:73], v[96:97], v[88:89]
	v_pk_fma_f32 v[94:95], v[78:79], v[102:103], v[94:95]
	v_pk_fma_f32 v[92:93], v[76:77], v[100:101], v[92:93]
	v_lshlrev_b32_e32 v96, 16, v12
	v_and_b32_e32 v97, 0xffff0000, v12
	v_lshlrev_b32_e32 v98, 16, v13
	v_and_b32_e32 v99, 0xffff0000, v13
	v_lshlrev_b32_e32 v100, 16, v14
	v_and_b32_e32 v101, 0xffff0000, v14
	v_lshlrev_b32_e32 v102, 16, v15
	v_and_b32_e32 v103, 0xffff0000, v15
	v_pk_fma_f32 v[82:83], v[74:75], v[98:99], v[82:83]
	v_pk_fma_f32 v[80:81], v[72:73], v[96:97], v[80:81]
	v_pk_fma_f32 v[86:87], v[78:79], v[102:103], v[86:87]
	v_pk_fma_f32 v[84:85], v[76:77], v[100:101], v[84:85]
	ds_read_b128 v[72:75], v222 offset:512
	ds_read_b128 v[76:79], v222 offset:528
	s_add_i32 s18, s33, 0x1ec00
	s_cmpk_eq_i32 s95, 0xf80
	s_waitcnt lgkmcnt(0)
	v_pk_fma_f32 v[88:89], v[72:73], v[96:97], v[88:89]
	v_pk_fma_f32 v[90:91], v[74:75], v[98:99], v[90:91]
	v_pk_fma_f32 v[92:93], v[76:77], v[100:101], v[92:93]
	v_pk_fma_f32 v[94:95], v[78:79], v[102:103], v[94:95]
	v_lshlrev_b32_e32 v96, 16, v16
	v_and_b32_e32 v97, 0xffff0000, v16
	v_lshlrev_b32_e32 v98, 16, v17
	v_and_b32_e32 v99, 0xffff0000, v17
	v_lshlrev_b32_e32 v100, 16, v18
	v_and_b32_e32 v101, 0xffff0000, v18
	v_lshlrev_b32_e32 v102, 16, v19
	v_and_b32_e32 v103, 0xffff0000, v19
	v_pk_fma_f32 v[80:81], v[72:73], v[96:97], v[80:81]
	v_pk_fma_f32 v[82:83], v[74:75], v[98:99], v[82:83]
	v_pk_fma_f32 v[84:85], v[76:77], v[100:101], v[84:85]
	v_pk_fma_f32 v[86:87], v[78:79], v[102:103], v[86:87]
	ds_read_b128 v[72:75], v222 offset:768
	ds_read_b128 v[76:79], v222 offset:784
	s_waitcnt lgkmcnt(0)
	v_pk_fma_f32 v[88:89], v[72:73], v[96:97], v[88:89]
	v_lshlrev_b32_e32 v96, 16, v20
	v_and_b32_e32 v97, 0xffff0000, v20
	v_pk_fma_f32 v[72:73], v[72:73], v[96:97], v[80:81]
	v_lshlrev_b32_e32 v80, 16, v22
	v_and_b32_e32 v81, 0xffff0000, v22
	v_pk_fma_f32 v[90:91], v[74:75], v[98:99], v[90:91]
	v_pk_fma_f32 v[92:93], v[76:77], v[100:101], v[92:93]
	v_lshlrev_b32_e32 v98, 16, v21
	v_and_b32_e32 v99, 0xffff0000, v21
	v_pk_fma_f32 v[76:77], v[76:77], v[80:81], v[84:85]
	v_mul_f32_e32 v80, 0xbfb8aa3b, v89
	v_pk_fma_f32 v[74:75], v[74:75], v[98:99], v[82:83]
	v_lshlrev_b32_e32 v82, 16, v23
	v_and_b32_e32 v83, 0xffff0000, v23
	v_exp_f32_e32 v81, v80
	v_mul_f32_e32 v80, 0xbfb8aa3b, v90
	v_pk_fma_f32 v[94:95], v[78:79], v[102:103], v[94:95]
	v_pk_fma_f32 v[78:79], v[78:79], v[82:83], v[86:87]
	v_exp_f32_e32 v82, v80
	v_mul_f32_e32 v80, 0xbfb8aa3b, v91
	v_exp_f32_e32 v83, v80
	v_mul_f32_e32 v80, 0xbfb8aa3b, v92
	v_exp_f32_e32 v84, v80
	v_mul_f32_e32 v80, 0xbfb8aa3b, v93
	v_exp_f32_e32 v85, v80
	v_mul_f32_e32 v80, 0xbfb8aa3b, v94
	v_exp_f32_e32 v86, v80
	v_mul_f32_e32 v80, 0xbfb8aa3b, v95
	v_exp_f32_e32 v87, v80
	v_mul_f32_e32 v80, 0xbfb8aa3b, v72
	v_exp_f32_e32 v96, v80
	v_mul_f32_e32 v80, 0xbfb8aa3b, v73
	v_mul_f32_e32 v2, 0xbfb8aa3b, v88
	v_exp_f32_e32 v97, v80
	v_mul_f32_e32 v80, 0xbfb8aa3b, v74
	v_exp_f32_e32 v2, v2
	v_exp_f32_e32 v98, v80
	v_mul_f32_e32 v80, 0xbfb8aa3b, v75
	v_exp_f32_e32 v99, v80
	v_mul_f32_e32 v80, 0xbfb8aa3b, v76
	v_exp_f32_e32 v100, v80
	v_mul_f32_e32 v80, 0xbfb8aa3b, v77
	v_exp_f32_e32 v101, v80
	v_mul_f32_e32 v80, 0xbfb8aa3b, v78
	v_exp_f32_e32 v102, v80
	v_mul_f32_e32 v80, 0xbfb8aa3b, v79
	v_add_f32_e32 v2, 1.0, v2
	v_exp_f32_e32 v103, v80
	v_rcp_f32_e32 v80, v2
	v_add_f32_e32 v2, 1.0, v81
	v_rcp_f32_e32 v81, v2
	v_add_f32_e32 v2, 1.0, v82
	v_rcp_f32_e32 v82, v2
	v_add_f32_e32 v2, 1.0, v83
	v_rcp_f32_e32 v83, v2
	v_add_f32_e32 v2, 1.0, v84
	v_rcp_f32_e32 v84, v2
	v_add_f32_e32 v2, 1.0, v85
	v_rcp_f32_e32 v85, v2
	v_add_f32_e32 v2, 1.0, v86
	v_rcp_f32_e32 v86, v2
	v_add_f32_e32 v2, 1.0, v87
	v_rcp_f32_e32 v87, v2
	v_add_f32_e32 v2, 1.0, v96
	v_rcp_f32_e32 v96, v2
	v_add_f32_e32 v2, 1.0, v97
	v_rcp_f32_e32 v97, v2
	v_add_f32_e32 v2, 1.0, v98
	v_rcp_f32_e32 v98, v2
	v_add_f32_e32 v2, 1.0, v99
	v_rcp_f32_e32 v99, v2
	v_add_f32_e32 v2, 1.0, v100
	v_rcp_f32_e32 v100, v2
	v_add_f32_e32 v2, 1.0, v101
	v_rcp_f32_e32 v101, v2
	v_add_f32_e32 v2, 1.0, v102
	v_rcp_f32_e32 v102, v2
	v_add_f32_e32 v2, 1.0, v103
	v_rcp_f32_e32 v103, v2
	v_pk_mul_f32 v[82:83], v[90:91], v[82:83]
	v_pk_mul_f32 v[80:81], v[88:89], v[80:81]
	v_pk_mul_f32 v[86:87], v[94:95], v[86:87]
	v_pk_mul_f32 v[84:85], v[92:93], v[84:85]
	v_pk_mul_f32 v[88:89], v[74:75], v[98:99]
	v_pk_mul_f32 v[90:91], v[72:73], v[96:97]
	v_cvt_pk_bf16_f32 v72, v80, v81
	v_cvt_pk_bf16_f32 v73, v82, v83
	v_cvt_pk_bf16_f32 v74, v84, v85
	v_cvt_pk_bf16_f32 v75, v86, v87
	ds_write_b128 v236, v[72:75]
	v_lshl_add_u32 v2, v201, 2, s18
	ds_read_b32 v2, v2
	v_pk_mul_f32 v[78:79], v[78:79], v[102:103]
	v_pk_mul_f32 v[76:77], v[76:77], v[100:101]
	s_waitcnt lgkmcnt(0)
; __device__ __forceinline__ unsigned cvt_pk_bf16(float lo, float hi) { unsigned r; asm volatile("v_cvt_pk_bf16_f32 %0, %1, %2" : "=v"(r) : "v"(lo), "v"(hi)); return r; }
; #define LAS __attribute__((address_space(3)))
; #define LDS_BARRIER() asm volatile("s_waitcnt lgkmcnt(0)\n\ts_barrier" ::: "memory")
; template <int VAR, bool SIDE> ...
;     ...
;         for (int rr = 0; rr < 2; ++rr) { const f32x4 oa = o2[rr][0], ob = o2[rr][1];
;             u32x4 w; w.x = cvt_pk_bf16(oa[0], oa[1]); w.y = cvt_pk_bf16(oa[2], oa[3]); w.z = cvt_pk_bf16(ob[0], ob[1]); w.w = cvt_pk_bf16(ob[2], ob[3]);
;             *(LAS u32x4*)(Xs + (xr0 + rr) * XS + xch * 16) = w;
;             const float f = wl[xr0 + rr]; const f32x4 pa = oa * f, pb = ob * f;
;             w.x = cvt_pk_bf16(pa[0], pa[1]); w.y = cvt_pk_bf16(pa[2], pa[3]); w.z = cvt_pk_bf16(pb[0], pb[1]); w.w = cvt_pk_bf16(pb[2], pb[3]);
;             *(LAS u32x4*)(Xw + (xr0 + rr) * XS + xch * 16) = w; }
; #pragma unroll
;         for (int i = 0; i < 8; ++i) *(LAS u32x4*)(bcdst + 16 * i * BS) = bcraw[i];
;         if (SIDE) { side_drain(sd0, sv0); sd0.mode = 0; }
;         LDS_BARRIER();
;         if (c + 1 < 32 && !(VAR & 2)) SSD_LOADS(c + 1);
	v_pk_mul_f32 v[74:75], v[2:3], v[82:83] op_sel_hi:[0,1]
	v_pk_mul_f32 v[72:73], v[2:3], v[80:81] op_sel_hi:[0,1]
	v_pk_mul_f32 v[80:81], v[2:3], v[86:87] op_sel_hi:[0,1]
	v_pk_mul_f32 v[82:83], v[2:3], v[84:85] op_sel_hi:[0,1]
	v_cvt_pk_bf16_f32 v72, v72, v73
	v_cvt_pk_bf16_f32 v73, v74, v75
	v_cvt_pk_bf16_f32 v74, v82, v83
	v_cvt_pk_bf16_f32 v75, v80, v81
	ds_write_b128 v236, v[72:75] offset:18432
	v_cvt_pk_bf16_f32 v72, v90, v91
	v_cvt_pk_bf16_f32 v73, v88, v89
	v_cvt_pk_bf16_f32 v74, v76, v77
	v_cvt_pk_bf16_f32 v75, v78, v79
	ds_write_b128 v237, v[72:75]
	v_lshl_add_u32 v2, v231, 2, s18
	ds_read_b32 v2, v2
	s_cselect_b64 s[18:19], -1, 0
	s_cmpk_lg_i32 s95, 0xf80
	s_cselect_b64 s[26:27], -1, 0
	s_and_b64 vcc, exec, s[18:19]
	s_waitcnt lgkmcnt(0)
	v_pk_mul_f32 v[74:75], v[88:89], v[2:3] op_sel_hi:[1,0]
	v_pk_mul_f32 v[72:73], v[90:91], v[2:3] op_sel_hi:[1,0]
	v_pk_mul_f32 v[78:79], v[78:79], v[2:3] op_sel_hi:[1,0]
	v_pk_mul_f32 v[76:77], v[76:77], v[2:3] op_sel_hi:[1,0]
	v_cvt_pk_bf16_f32 v72, v72, v73
	v_cvt_pk_bf16_f32 v73, v74, v75
	s_nop 0
	v_cvt_pk_bf16_f32 v74, v76, v77
	v_cvt_pk_bf16_f32 v75, v78, v79
	ds_write_b128 v237, v[72:75] offset:18432
	s_waitcnt vmcnt(0)
	ds_write_b128 v238, v[24:27]
	ds_write_b128 v238, v[28:31] offset:4352
	ds_write_b128 v238, v[32:35] offset:8704
	ds_write_b128 v238, v[36:39] offset:13056
	ds_write_b128 v238, v[40:43] offset:17408
	ds_write_b128 v238, v[44:47] offset:21760
	s_waitcnt vmcnt(0)
	ds_write_b128 v238, v[48:51] offset:26112
	ds_write_b128 v238, v[52:55] offset:30464
	s_waitcnt lgkmcnt(0)
	s_barrier
	s_cbranch_vccnz .LBB0_414
	v_add_u32_e32 v2, s95, v234
	v_add_u32_e32 v4, 0x7d, v2
	v_mov_b64_e32 v[20:21], s[66:67]
	v_mad_i64_i32 v[4:5], s[48:49], v4, s69, v[20:21]
	v_mov_b32_e32 v107, v3
	v_lshl_add_u64 v[4:5], v[4:5], 0, v[106:107]
	v_add_u32_e32 v6, 0x7e, v2
	v_add_co_u32_e32 v4, vcc, 0x4000, v4
	v_mad_i64_i32 v[6:7], s[48:49], v6, s69, v[20:21]
	s_nop 0
	v_addc_co_u32_e32 v5, vcc, 0, v5, vcc
	v_lshl_add_u64 v[6:7], v[6:7], 0, v[106:107]
	v_add_u32_e32 v12, 0x7f, v2
	v_add_co_u32_e32 v6, vcc, 0x4000, v6
	v_mad_i64_i32 v[12:13], s[48:49], v12, s69, v[20:21]
	s_nop 0
	v_addc_co_u32_e32 v7, vcc, 0, v7, vcc
	v_lshl_add_u64 v[12:13], v[12:13], 0, v[106:107]
	v_add_u32_e32 v14, 0x80, v2
	v_add_co_u32_e32 v12, vcc, 0x4000, v12
	v_mad_i64_i32 v[14:15], s[48:49], v14, s69, v[20:21]
	s_nop 0
	v_addc_co_u32_e32 v13, vcc, 0, v13, vcc
	v_lshl_add_u64 v[14:15], v[14:15], 0, v[106:107]
	v_add_u32_e32 v2, 0x81, v2
	v_add_co_u32_e32 v16, vcc, 0x4000, v14
	v_mad_i64_i32 v[20:21], s[48:49], v2, s69, v[20:21]
	s_nop 0
	v_addc_co_u32_e32 v17, vcc, 0, v15, vcc
	v_lshl_add_u64 v[20:21], v[20:21], 0, v[106:107]
	v_add_co_u32_e32 v20, vcc, 0x4000, v20
	global_load_dwordx4 v[8:11], v[4:5], off offset:1024
	s_nop 0
	global_load_dwordx4 v[4:7], v[6:7], off offset:1024
	v_addc_co_u32_e32 v21, vcc, 0, v21, vcc
	global_load_dwordx4 v[12:15], v[12:13], off offset:1024
	s_nop 0
	global_load_dwordx4 v[16:19], v[16:17], off offset:1024
	s_andn2_b64 vcc, exec, s[0:1]
	global_load_dwordx4 v[20:23], v[20:21], off offset:1024
	s_cbranch_vccnz .LBB0_414
	v_add_u32_e32 v2, s95, v233
	v_add_u32_e32 v72, 0x80, v2
	v_ashrrev_i32_e32 v73, 31, v72
	v_lshlrev_b64 v[72:73], 8, v[72:73]
	v_lshl_add_u64 v[72:73], s[6:7], 0, v[72:73]
	global_load_dword v211, v[72:73], off
	v_add_u32_e32 v72, 0xc0, v2
	v_ashrrev_i32_e32 v73, 31, v72
	v_lshlrev_b64 v[72:73], 8, v[72:73]
	v_lshl_add_u64 v[72:73], s[6:7], 0, v[72:73]
	global_load_dword v212, v[72:73], off
; template <int VAR, bool SIDE> ...
;     ...
;             const int lt = wave < 4 ? wave : 11 - wave;
;             const int l = 16 * lt + l15; const float acl = acum[l];
;             const size_t token = (size_t)(tok0 + l);
;             bf16_t* zp = P + token * NPROJ + COL_Z + hd * 64 + 4 * q4;
;             u32x2 zv[4];
; #pragma unroll
;             for (int pt = 0; pt < 4; ++pt) { zv[pt] = (u32x2){0x3f803f80u, 0x3f803f80u}; if (!(VAR & 1)) zv[pt] = *(const u32x2*)(zp + 16 * pt); }
;             f32x4 Y[4];
; #pragma unroll
;             for (int pt = 0; pt < 4; ++pt) Y[pt] = (f32x4){0.f, 0.f, 0.f, 0.f};
;             bf16x8 Cf[4];
;             LAS unsigned char* cbase = Cm + l * BS + q4 * 16;
; #pragma unroll
;             for (int ks = 0; ks < 4; ++ks) Cf[ks] = *(const LAS bf16x8*)(cbase + ks * 64);
;             LAS unsigned char* hbase = Hs + l15 * BS + q4 * 16;
; #pragma unroll
;             for (int pt = 0; pt < 4; ++pt)
; #pragma unroll
;                 for (int ks = 0; ks < 4; ++ks) { const bf16x8 Hf = *(const LAS bf16x8*)(hbase + pt * 16 * BS + ks * 64); Y[pt] = mfma16(Hf, Cf[ks], Y[pt]); }
;             const float eal = __builtin_amdgcn_exp2f(acl);
; #pragma unroll
;             for (int pt = 0; pt < 4; ++pt) Y[pt] *= eal;
;             __builtin_amdgcn_sched_barrier(0);
;             f32x4 Gt[8];
;             f32x4 penv;
; #pragma unroll
;             for (int e = 0; e < 4; ++e) penv[e] = (4 * q4 + e <= l15) ? 0.f : 1e30f;
;             LAS unsigned char* bbase = Bm + l15 * BS + q4 * 16;
; #pragma unroll
;             for (int st = 0; st < 8; ++st) { Gt[st] = (f32x4){0.f, 0.f, 0.f, 0.f};
;                 if (st <= lt) {
; #pragma unroll
;                     for (int ks = 0; ks < 4; ++ks) { const bf16x8 Bf = *(const LAS bf16x8*)(bbase + st * 16 * BS + ks * 64); Gt[st] = mfma16(Bf, Cf[ks], Gt[st]); }
;                     const f32x4 as = *(const LAS f32x4*)(acum + 16 * st + 4 * q4), ds = *(const LAS f32x4*)(dtv + 16 * st + 4 * q4);
; #pragma unroll
;                     for (int e = 0; e < 1; ++e) { const float flagf = (st == lt) ? 1.0f : 0.0f;
;                         const f32x4 dv = (acl - as) - penv * flagf;
;                         f32x4 fv; fv[0] = __builtin_amdgcn_exp2f(dv[0]); fv[1] = __builtin_amdgcn_exp2f(dv[1]); fv[2] = __builtin_amdgcn_exp2f(dv[2]); fv[3] = __builtin_amdgcn_exp2f(dv[3]);
.LBB0_414:
	s_add_i32 s33, s33, 0x1e800
	v_lshl_add_u32 v2, v223, 2, s33
	ds_read_b32 v105, v2
	v_add_u32_e32 v2, s95, v235
	v_mov_b64_e32 v[72:73], s[66:67]
	v_mad_i64_i32 v[72:73], s[48:49], v2, s69, v[72:73]
	v_lshl_add_u64 v[72:73], v[72:73], 0, s[30:31]
	v_lshlrev_b32_e32 v2, 1, v108
	v_lshl_add_u64 v[72:73], v[72:73], 0, v[2:3]
	s_mov_b64 s[48:49], 0x2400
	v_lshl_add_u64 v[144:145], v[72:73], 0, s[48:49]
	v_add_co_u32_e32 v72, vcc, s70, v72
	s_nop 1
	v_addc_co_u32_e32 v73, vcc, 0, v73, vcc
	global_load_dwordx2 v[152:153], v[72:73], off offset:1024
	global_load_dwordx2 v[150:151], v[144:145], off offset:32
	global_load_dwordx2 v[148:149], v[144:145], off offset:64
	global_load_dwordx2 v[146:147], v[144:145], off offset:96
	ds_read_b128 v[88:91], v239
	ds_read_b128 v[84:87], v239 offset:64
	ds_read_b128 v[80:83], v239 offset:128
	ds_read_b128 v[72:75], v239 offset:192
	ds_read_b128 v[76:79], v240
	ds_read_b128 v[92:95], v240 offset:64
	ds_read_b128 v[96:99], v240 offset:4416
	s_waitcnt lgkmcnt(0)
	v_mfma_f32_16x16x32_bf16 v[76:79], v[76:79], v[88:91], 0
	ds_read_b128 v[100:103], v240 offset:8768
	ds_read_b128 v[154:157], v240 offset:13120
	v_mfma_f32_16x16x32_bf16 v[76:79], v[92:95], v[84:87], v[76:79]
	ds_read_b128 v[92:95], v240 offset:128
	s_waitcnt lgkmcnt(0)
	v_mfma_f32_16x16x32_bf16 v[76:79], v[92:95], v[80:83], v[76:79]
	ds_read_b128 v[92:95], v240 offset:192
	s_waitcnt lgkmcnt(0)
	v_mfma_f32_16x16x32_bf16 v[76:79], v[92:95], v[72:75], v[76:79]
	ds_read_b128 v[92:95], v240 offset:4352
	s_waitcnt lgkmcnt(0)
	v_mfma_f32_16x16x32_bf16 v[92:95], v[92:95], v[88:91], 0
	v_mfma_f32_16x16x32_bf16 v[92:95], v[96:99], v[84:87], v[92:95]
	ds_read_b128 v[96:99], v240 offset:4480
	s_waitcnt lgkmcnt(0)
	v_mfma_f32_16x16x32_bf16 v[92:95], v[96:99], v[80:83], v[92:95]
	ds_read_b128 v[96:99], v240 offset:4544
	s_waitcnt lgkmcnt(0)
	v_mfma_f32_16x16x32_bf16 v[92:95], v[96:99], v[72:75], v[92:95]
	ds_read_b128 v[96:99], v240 offset:8704
	s_waitcnt lgkmcnt(0)
	v_mfma_f32_16x16x32_bf16 v[96:99], v[96:99], v[88:91], 0
	v_mfma_f32_16x16x32_bf16 v[96:99], v[100:103], v[84:87], v[96:99]
	ds_read_b128 v[100:103], v240 offset:8832
	s_waitcnt lgkmcnt(0)
	v_mfma_f32_16x16x32_bf16 v[96:99], v[100:103], v[80:83], v[96:99]
	ds_read_b128 v[100:103], v240 offset:8896
	s_waitcnt lgkmcnt(0)
	v_mfma_f32_16x16x32_bf16 v[96:99], v[100:103], v[72:75], v[96:99]
	ds_read_b128 v[100:103], v240 offset:13056
	s_waitcnt lgkmcnt(0)
	v_mfma_f32_16x16x32_bf16 v[100:103], v[100:103], v[88:91], 0
	v_mfma_f32_16x16x32_bf16 v[100:103], v[154:157], v[84:87], v[100:103]
	ds_read_b128 v[154:157], v240 offset:13184
	s_waitcnt lgkmcnt(0)
	v_mfma_f32_16x16x32_bf16 v[100:103], v[154:157], v[80:83], v[100:103]
	ds_read_b128 v[154:157], v240 offset:13248
	s_waitcnt lgkmcnt(0)
	v_mfma_f32_16x16x32_bf16 v[100:103], v[154:157], v[72:75], v[100:103]
	v_cndmask_b32_e64 v155, 0, 1, s[4:5]
	v_lshl_add_u32 v107, v108, 2, s33
	v_add_u32_e32 v2, s46, v226
	v_mov_b32_e32 v154, 0
	v_cmp_ne_u32_e64 s[46:47], 1, v155
	s_andn2_b64 vcc, exec, s[4:5]
	v_mov_b32_e32 v158, 0
	v_mov_b32_e32 v159, 0
	v_mov_b32_e32 v156, 0
	v_mov_b32_e32 v157, 0
	s_cbranch_vccnz .LBB0_416
	ds_read_b128 v[156:159], v224 offset:36864
	ds_read_b128 v[160:163], v224 offset:36928
	s_waitcnt lgkmcnt(0)
	v_mfma_f32_16x16x32_bf16 v[156:159], v[156:159], v[88:91], 0
	v_mfma_f32_16x16x32_bf16 v[156:159], v[160:163], v[84:87], v[156:159]
	ds_read_b128 v[160:163], v224 offset:36992
	s_waitcnt lgkmcnt(0)
	v_mfma_f32_16x16x32_bf16 v[156:159], v[160:163], v[80:83], v[156:159]
	ds_read_b128 v[160:163], v224 offset:37056
	s_waitcnt lgkmcnt(0)
	v_mfma_f32_16x16x32_bf16 v[158:161], v[160:163], v[72:75], v[156:159]
	ds_read_b128 v[162:165], v107
	ds_read_b128 v[182:185], v2
	s_waitcnt lgkmcnt(0)
	v_sub_f32_e32 v155, v105, v162
	s_nop 0
	v_sub_f32_e32 v156, v105, v163
	v_sub_f32_e32 v157, v105, v164
	v_sub_f32_e32 v162, v105, v165
	v_sub_f32_e32 v163, v162, v115
	v_sub_f32_e32 v162, v157, v114
	v_sub_f32_e32 v157, v156, v113
	v_sub_f32_e32 v155, v155, v112
	v_exp_f32_e32 v156, v155
	v_exp_f32_e32 v157, v157
	v_exp_f32_e32 v162, v162
	v_exp_f32_e32 v163, v163
	v_pk_mul_f32 v[164:165], v[182:183], v[156:157]
	s_nop 0
	v_pk_mul_f32 v[158:159], v[158:159], v[164:165]
	v_pk_mul_f32 v[156:157], v[184:185], v[162:163]
	s_nop 0
	v_pk_mul_f32 v[156:157], v[160:161], v[156:157]

; #define LAS __attribute__((address_space(3)))
; #define SSD_LOADS_BC(c_) do { const int tok0_ = b * SEQ + (c_) * 128; \
;         _Pragma("unroll") for (int i = 0; i < 8; ++i) bcraw[i] = *(const u32x4*)(HBC + (size_t)(tok0_ + bcrow + 16 * i) * 2048 + bccol); } while (0)
; template <int VAR, bool SIDE> ...
;     ...
;             if (c + 1 < 32 && !(VAR & 2)) SSD_LOADS_BC(c + 1);
;             if (SIDE) { sd0 = side_decode(sa, 1, sgw + sngw * c, lane); side_issue(sd0, sv0); }
; #pragma unroll
;             for (int pt = 0; pt < 4; ++pt) { const int p0 = 16 * pt + 4 * q4;
;                 const u32x2 xv = *(const LAS u32x2*)(Xs + l * XS + p0 * 2);
.LBB0_435:
	s_andn2_b64 vcc, exec, s[26:27]
	s_cbranch_vccnz .Lssd_nopf
	v_add_u32_e32 v50, s95, v232
	v_add_u32_e32 v24, 0x80, v50
	v_add_u32_e32 v26, 0x90, v50
	v_add_u32_e32 v32, 0xa0, v50
	v_add_u32_e32 v34, 0xb0, v50
	v_add_u32_e32 v40, 0xc0, v50
	v_add_u32_e32 v42, 0xd0, v50
	v_add_u32_e32 v48, 0xe0, v50
	v_add_u32_e32 v50, 0xf0, v50
	v_ashrrev_i32_e32 v25, 31, v24
	v_ashrrev_i32_e32 v27, 31, v26
	v_ashrrev_i32_e32 v33, 31, v32
	v_ashrrev_i32_e32 v35, 31, v34
	v_ashrrev_i32_e32 v41, 31, v40
	v_ashrrev_i32_e32 v43, 31, v42
	v_ashrrev_i32_e32 v49, 31, v48
	v_ashrrev_i32_e32 v51, 31, v50
	v_lshlrev_b64 v[24:25], 12, v[24:25]
	v_lshlrev_b64 v[26:27], 12, v[26:27]
	v_lshlrev_b64 v[32:33], 12, v[32:33]
	v_lshlrev_b64 v[34:35], 12, v[34:35]
	v_lshlrev_b64 v[40:41], 12, v[40:41]
	v_lshlrev_b64 v[42:43], 12, v[42:43]
	v_lshlrev_b64 v[48:49], 12, v[48:49]
	v_lshlrev_b64 v[50:51], 12, v[50:51]
	v_lshl_add_u64 v[24:25], v[0:1], 0, v[24:25]
	v_lshl_add_u64 v[28:29], v[0:1], 0, v[26:27]
	v_lshl_add_u64 v[32:33], v[0:1], 0, v[32:33]
	v_lshl_add_u64 v[36:37], v[0:1], 0, v[34:35]
	v_lshl_add_u64 v[40:41], v[0:1], 0, v[40:41]
	v_lshl_add_u64 v[44:45], v[0:1], 0, v[42:43]
	v_lshl_add_u64 v[48:49], v[0:1], 0, v[48:49]
	v_lshl_add_u64 v[52:53], v[0:1], 0, v[50:51]
	global_load_dwordx4 v[24:27], v[24:25], off
	s_nop 0
	global_load_dwordx4 v[28:31], v[28:29], off
	s_nop 0
	global_load_dwordx4 v[32:35], v[32:33], off
	s_nop 0
	global_load_dwordx4 v[36:39], v[36:37], off
	s_nop 0
	global_load_dwordx4 v[40:43], v[40:41], off
	s_nop 0
	global_load_dwordx4 v[44:47], v[44:45], off
	s_nop 0
	global_load_dwordx4 v[48:51], v[48:49], off
	s_nop 0
	global_load_dwordx4 v[52:55], v[52:53], off
	ds_read_b64 v[88:89], v241
	s_waitcnt vmcnt(8)
	s_branch .Lssd_pfdone

; __device__ __forceinline__ unsigned cvt_pk_bf16(float lo, float hi) { unsigned r; asm volatile("v_cvt_pk_bf16_f32 %0, %1, %2" : "=v"(r) : "v"(lo), "v"(hi)); return r; }
; __device__ __forceinline__ float bflo(unsigned u) { return __uint_as_float(u << 16); }
; __device__ __forceinline__ float bfhi(unsigned u) { return __uint_as_float(u & 0xffff0000u); }
; #define LAS __attribute__((address_space(3)))
; __device__ __forceinline__ s16x4 ldtr(LAS unsigned char* p) { return __builtin_bit_cast(s16x4, __builtin_amdgcn_ds_read_tr16_b64_v4i16((LAS v4i16_t*)p)); }
; __device__ __forceinline__ bf16x8 cat8(s16x4 lo, s16x4 hi) { return (bf16x8){lo[0], lo[1], lo[2], lo[3], hi[0], hi[1], hi[2], hi[3]}; }
; template <int VAR, bool SIDE> ...
;     ...
;             for (int pt = 0; pt < 4; ++pt) { const int p0 = 16 * pt + 4 * q4;
;                 const u32x2 xv = *(const LAS u32x2*)(Xs + l * XS + p0 * 2);
;                 const f32x4 xf = {bflo(xv.x), bfhi(xv.x), bflo(xv.y), bfhi(xv.y)}, zf = {bflo(zv[pt].x), bfhi(zv[pt].x), bflo(zv[pt].y), bfhi(zv[pt].y)};
;                 const f32x4 yv = (Y[pt] + Dk * xf) * zf;
;                 u32x2 pk; pk.x = cvt_pk_bf16(yv[0], yv[1]); pk.y = cvt_pk_bf16(yv[2], yv[3]); if (!(VAR & 1)) *(u32x2*)(zp + 16 * pt) = pk; else asm volatile("" :: "v"(pk.x), "v"(pk.y)); }
;             __builtin_amdgcn_sched_barrier(0);
;             const float et = __builtin_amdgcn_exp2f(acum[127]);
; #pragma unroll
;             for (int pt = 0; pt < 4; ++pt) hacc[pt] *= et;
;             LAS unsigned char* btbase = Bm + (4 * q4 + (l15 >> 2)) * BS + (16 * wave + 4 * (l15 & 3)) * 2;
;             LAS unsigned char* xwbase = Xw + (4 * q4 + (l15 >> 2)) * XS + (l15 & 3) * 8;
; #pragma unroll
;             for (int kk = 0; kk < 4; ++kk) {
;                 const s16x4 blo = ldtr(btbase + (32 * kk) * BS);
;                 const s16x4 bhi = ldtr(btbase + (32 * kk + 16) * BS);
;                 const bf16x8 Bf = cat8(blo, bhi);
; #pragma unroll
;                 for (int pt = 0; pt < 4; ++pt) {
;                     const s16x4 xlo = ldtr(xwbase + (32 * kk) * XS + pt * 32);
;                     const s16x4 xhi = ldtr(xwbase + (32 * kk + 16) * XS + pt * 32);
;                     hacc[pt] = mfma16(Bf, cat8(xlo, xhi), hacc[pt]); }
;             }
.Lssd_pfdone:
	v_lshlrev_b32_e32 v90, 16, v152
	v_and_b32_e32 v91, 0xffff0000, v152
	v_mov_b32_e32 v105, v104
	v_lshlrev_b32_e32 v94, 16, v153
	s_waitcnt lgkmcnt(0)
	v_lshlrev_b32_e32 v92, 16, v88
	v_and_b32_e32 v93, 0xffff0000, v88
	v_lshlrev_b32_e32 v88, 16, v89
	v_and_b32_e32 v89, 0xffff0000, v89
	v_pk_fma_f32 v[84:85], v[110:111], v[92:93], v[84:85]
	v_and_b32_e32 v95, 0xffff0000, v153
	v_pk_fma_f32 v[86:87], v[104:105], v[88:89], v[86:87]
	v_pk_mul_f32 v[84:85], v[84:85], v[90:91]
	v_pk_mul_f32 v[86:87], v[86:87], v[94:95]
	v_cvt_pk_bf16_f32 v84, v84, v85
	v_lshlrev_b32_e32 v88, 16, v150
	v_cvt_pk_bf16_f32 v85, v86, v87
	global_store_dwordx2 v[144:145], v[84:85], off
	ds_read_b64 v[84:85], v241 offset:32
	v_and_b32_e32 v89, 0xffff0000, v150
	v_lshlrev_b32_e32 v90, 16, v151
	v_and_b32_e32 v91, 0xffff0000, v151
	s_waitcnt lgkmcnt(0)
	v_lshlrev_b32_e32 v86, 16, v84
	v_and_b32_e32 v87, 0xffff0000, v84
	v_lshlrev_b32_e32 v84, 16, v85
	v_and_b32_e32 v85, 0xffff0000, v85
	v_pk_fma_f32 v[80:81], v[110:111], v[86:87], v[80:81]
	v_pk_fma_f32 v[82:83], v[104:105], v[84:85], v[82:83]
	v_pk_mul_f32 v[80:81], v[80:81], v[88:89]
	v_pk_mul_f32 v[82:83], v[82:83], v[90:91]
	v_cvt_pk_bf16_f32 v80, v80, v81
	v_lshlrev_b32_e32 v84, 16, v148
	v_cvt_pk_bf16_f32 v81, v82, v83
	global_store_dwordx2 v[144:145], v[80:81], off offset:32
	ds_read_b64 v[80:81], v241 offset:64
	v_and_b32_e32 v85, 0xffff0000, v148
	v_lshlrev_b32_e32 v86, 16, v149
	v_and_b32_e32 v87, 0xffff0000, v149
	s_waitcnt lgkmcnt(0)
	v_lshlrev_b32_e32 v82, 16, v80
	v_and_b32_e32 v83, 0xffff0000, v80
	v_lshlrev_b32_e32 v80, 16, v81
	v_and_b32_e32 v81, 0xffff0000, v81
	v_pk_fma_f32 v[76:77], v[110:111], v[82:83], v[76:77]
	v_pk_fma_f32 v[78:79], v[104:105], v[80:81], v[78:79]
	v_pk_mul_f32 v[76:77], v[76:77], v[84:85]
	v_pk_mul_f32 v[78:79], v[78:79], v[86:87]
	v_cvt_pk_bf16_f32 v76, v76, v77
	v_lshlrev_b32_e32 v80, 16, v146
	v_cvt_pk_bf16_f32 v77, v78, v79
	global_store_dwordx2 v[144:145], v[76:77], off offset:64
	ds_read_b64 v[76:77], v241 offset:96
	v_and_b32_e32 v81, 0xffff0000, v146
	v_lshlrev_b32_e32 v82, 16, v147
	v_and_b32_e32 v83, 0xffff0000, v147
	s_waitcnt lgkmcnt(0)
	v_lshlrev_b32_e32 v78, 16, v76
	v_and_b32_e32 v79, 0xffff0000, v76
	v_lshlrev_b32_e32 v76, 16, v77
	v_and_b32_e32 v77, 0xffff0000, v77
	v_pk_fma_f32 v[72:73], v[110:111], v[78:79], v[72:73]
	v_pk_fma_f32 v[74:75], v[104:105], v[76:77], v[74:75]
	v_pk_mul_f32 v[72:73], v[72:73], v[80:81]
	v_pk_mul_f32 v[74:75], v[74:75], v[82:83]
	v_cvt_pk_bf16_f32 v72, v72, v73
	s_nop 0
	v_cvt_pk_bf16_f32 v73, v74, v75
	global_store_dwordx2 v[144:145], v[72:73], off offset:96
	v_mov_b32_e32 v72, s33
	ds_read_b32 v72, v72 offset:508
	s_or_b64 s[18:19], s[78:79], s[18:19]
	s_and_b64 vcc, exec, s[18:19]
	s_waitcnt lgkmcnt(0)
	v_exp_f32_e32 v72, v72
	s_nop 0
	v_pk_mul_f32 v[58:59], v[58:59], v[72:73] op_sel_hi:[1,0]
	v_pk_mul_f32 v[56:57], v[56:57], v[72:73] op_sel_hi:[1,0]
	v_pk_mul_f32 v[62:63], v[62:63], v[72:73] op_sel_hi:[1,0]
	v_pk_mul_f32 v[60:61], v[60:61], v[72:73] op_sel_hi:[1,0]
	v_pk_mul_f32 v[66:67], v[66:67], v[72:73] op_sel_hi:[1,0]
	v_pk_mul_f32 v[64:65], v[64:65], v[72:73] op_sel_hi:[1,0]
	v_pk_mul_f32 v[70:71], v[70:71], v[72:73] op_sel_hi:[1,0]
	v_pk_mul_f32 v[68:69], v[68:69], v[72:73] op_sel_hi:[1,0]
	ds_read_b64_tr_b16 v[72:73], v229 offset:36864
	ds_read_b64_tr_b16 v[74:75], v229 offset:41216
	ds_read_b64_tr_b16 v[78:79], v2 offset:20736
	ds_read_b64_tr_b16 v[76:77], v2 offset:18432
	ds_read_b64_tr_b16 v[80:81], v2 offset:18464
	s_waitcnt lgkmcnt(0)
	v_mfma_f32_16x16x32_bf16 v[56:59], v[72:75], v[76:79], v[56:59]
	ds_read_b64_tr_b16 v[82:83], v2 offset:20768
	ds_read_b64_tr_b16 v[76:77], v2 offset:18496
	ds_read_b64_tr_b16 v[78:79], v2 offset:20800
	s_waitcnt lgkmcnt(0)
	v_mfma_f32_16x16x32_bf16 v[64:67], v[72:75], v[76:79], v[64:67]
	ds_read_b64_tr_b16 v[76:77], v2 offset:18528
	ds_read_b64_tr_b16 v[78:79], v2 offset:20832
	v_mfma_f32_16x16x32_bf16 v[60:63], v[72:75], v[80:83], v[60:63]
	s_waitcnt lgkmcnt(0)
	v_mfma_f32_16x16x32_bf16 v[68:71], v[72:75], v[76:79], v[68:71]
	ds_read_b64_tr_b16 v[72:73], v229 offset:45568
	ds_read_b64_tr_b16 v[74:75], v229 offset:49920
	ds_read_b64_tr_b16 v[76:77], v2 offset:23040
	ds_read_b64_tr_b16 v[78:79], v2 offset:25344
	s_waitcnt lgkmcnt(0)
	v_mfma_f32_16x16x32_bf16 v[56:59], v[72:75], v[76:79], v[56:59]
	ds_read_b64_tr_b16 v[76:77], v2 offset:23072
	ds_read_b64_tr_b16 v[78:79], v2 offset:25376
	s_waitcnt lgkmcnt(0)
	v_mfma_f32_16x16x32_bf16 v[60:63], v[72:75], v[76:79], v[60:63]
	ds_read_b64_tr_b16 v[76:77], v2 offset:23104
	ds_read_b64_tr_b16 v[78:79], v2 offset:25408
	s_waitcnt lgkmcnt(0)
	v_mfma_f32_16x16x32_bf16 v[64:67], v[72:75], v[76:79], v[64:67]
	ds_read_b64_tr_b16 v[76:77], v2 offset:23136
	ds_read_b64_tr_b16 v[78:79], v2 offset:25440
	s_waitcnt lgkmcnt(0)
	v_mfma_f32_16x16x32_bf16 v[68:71], v[72:75], v[76:79], v[68:71]
	ds_read_b64_tr_b16 v[72:73], v229 offset:54272
	ds_read_b64_tr_b16 v[74:75], v229 offset:58624
	ds_read_b64_tr_b16 v[76:77], v2 offset:27648
	ds_read_b64_tr_b16 v[78:79], v2 offset:29952
	s_waitcnt lgkmcnt(0)
	v_mfma_f32_16x16x32_bf16 v[56:59], v[72:75], v[76:79], v[56:59]
	ds_read_b64_tr_b16 v[76:77], v2 offset:27680
	ds_read_b64_tr_b16 v[78:79], v2 offset:29984
	s_waitcnt lgkmcnt(0)
	v_mfma_f32_16x16x32_bf16 v[60:63], v[72:75], v[76:79], v[60:63]
	ds_read_b64_tr_b16 v[76:77], v2 offset:27712
	ds_read_b64_tr_b16 v[78:79], v2 offset:30016
	s_waitcnt lgkmcnt(0)
	v_mfma_f32_16x16x32_bf16 v[64:67], v[72:75], v[76:79], v[64:67]
	ds_read_b64_tr_b16 v[76:77], v2 offset:27744
	ds_read_b64_tr_b16 v[78:79], v2 offset:30048
	s_waitcnt lgkmcnt(0)
	v_mfma_f32_16x16x32_bf16 v[68:71], v[72:75], v[76:79], v[68:71]
	ds_read_b64_tr_b16 v[72:73], v229 offset:62976
	ds_read_b64_tr_b16 v[74:75], v230 offset:30464
	ds_read_b64_tr_b16 v[76:77], v2 offset:32256
	ds_read_b64_tr_b16 v[78:79], v2 offset:34560
	s_waitcnt lgkmcnt(0)
	v_mfma_f32_16x16x32_bf16 v[56:59], v[72:75], v[76:79], v[56:59]
	ds_read_b64_tr_b16 v[76:77], v2 offset:32288
	ds_read_b64_tr_b16 v[78:79], v2 offset:34592
	s_waitcnt lgkmcnt(0)
	v_mfma_f32_16x16x32_bf16 v[60:63], v[72:75], v[76:79], v[60:63]
	ds_read_b64_tr_b16 v[76:77], v2 offset:32320
	ds_read_b64_tr_b16 v[78:79], v2 offset:34624
	s_waitcnt lgkmcnt(0)
	v_mfma_f32_16x16x32_bf16 v[64:67], v[72:75], v[76:79], v[64:67]
	ds_read_b64_tr_b16 v[76:77], v2 offset:32352
	ds_read_b64_tr_b16 v[78:79], v2 offset:34656
	s_waitcnt lgkmcnt(0)
	v_mfma_f32_16x16x32_bf16 v[68:71], v[72:75], v[76:79], v[68:71]
	s_cbranch_vccnz .LBB0_410
	v_add_f32_e32 v2, v200, v211
	v_cmp_nlt_f32_e32 vcc, s28, v2
	s_and_saveexec_b64 s[18:19], vcc
	s_cbranch_execz .LBB0_440
	v_mul_f32_e32 v72, 0x3fb8aa3b, v2
	v_rndne_f32_e32 v73, v72
	v_sub_f32_e32 v74, v72, v73
	v_fma_f32 v72, v2, s68, -v72
	v_fmac_f32_e32 v72, 0x32a5705f, v2
	v_add_f32_e32 v72, v74, v72
	v_cvt_i32_f32_e32 v73, v73
	v_exp_f32_e32 v72, v72
	v_cmp_ngt_f32_e32 vcc, s73, v2
	v_ldexp_f32 v72, v72, v73
	s_nop 0
	v_cndmask_b32_e32 v72, 0, v72, vcc
	v_cmp_nlt_f32_e32 vcc, s65, v2
	s_nop 1
	v_cndmask_b32_e32 v2, v208, v72, vcc
	v_add_f32_e32 v74, 1.0, v2
	v_add_f32_e32 v72, -1.0, v74
	v_sub_f32_e32 v73, v72, v74
	v_add_f32_e32 v73, 1.0, v73
	v_sub_f32_e32 v72, v2, v72
	v_add_f32_e32 v75, v72, v73
	v_frexp_mant_f32_e32 v76, v74
	v_cvt_f64_f32_e32 v[72:73], v74
	v_frexp_exp_i32_f64_e32 v72, v[72:73]
	v_cmp_gt_f32_e32 vcc, s29, v76
	s_nop 1
	v_subbrev_co_u32_e32 v80, vcc, 0, v72, vcc
	v_sub_u32_e32 v72, 0, v80
	v_ldexp_f32 v73, v74, v72
	v_add_f32_e32 v74, -1.0, v73
	v_add_f32_e32 v76, 1.0, v73
	v_ldexp_f32 v72, v75, v72
	v_add_f32_e32 v75, 1.0, v74
	v_add_f32_e32 v77, -1.0, v76
	v_sub_f32_e32 v75, v73, v75
	v_sub_f32_e32 v73, v73, v77
	v_add_f32_e32 v75, v72, v75
	v_add_f32_e32 v72, v72, v73
	v_add_f32_e32 v81, v76, v72
	v_rcp_f32_e32 v83, v81
	v_sub_f32_e32 v73, v76, v81
	v_add_f32_e32 v82, v72, v73
	v_add_f32_e32 v73, v74, v75
	v_mul_f32_e32 v85, v73, v83
	v_sub_f32_e32 v72, v74, v73
	v_mul_f32_e32 v74, v81, v85
	v_fma_f32 v76, v85, v81, -v74
	v_fmac_f32_e32 v76, v85, v82
	v_add_f32_e32 v84, v75, v72
	v_add_f32_e32 v72, v74, v76
	v_sub_f32_e32 v75, v73, v72
	v_pk_add_f32 v[78:79], v[72:73], v[74:75] neg_lo:[0,1] neg_hi:[0,1]
	v_mov_b32_e32 v77, v72
	v_pk_add_f32 v[72:73], v[78:79], v[76:77] neg_lo:[0,1] neg_hi:[0,1]
	v_cmp_neq_f32_e32 vcc, s72, v2
	v_add_f32_e32 v73, v84, v73
	v_add_f32_e32 v72, v72, v73
	v_add_f32_e32 v73, v75, v72
	v_mul_f32_e32 v84, v83, v73
	v_mul_f32_e32 v74, v81, v84
	v_fma_f32 v76, v84, v81, -v74
	v_fmac_f32_e32 v76, v84, v82
	v_sub_f32_e32 v75, v75, v73
	v_add_f32_e32 v81, v72, v75
	v_add_f32_e32 v72, v74, v76
	v_sub_f32_e32 v75, v73, v72
	v_pk_add_f32 v[78:79], v[72:73], v[74:75] neg_lo:[0,1] neg_hi:[0,1]
	v_mov_b32_e32 v77, v72
	v_pk_add_f32 v[72:73], v[78:79], v[76:77] neg_lo:[0,1] neg_hi:[0,1]
	s_nop 0
	v_add_f32_e32 v73, v81, v73
	v_add_f32_e32 v72, v72, v73
	v_add_f32_e32 v73, v85, v84
	v_add_f32_e32 v72, v75, v72
	v_sub_f32_e32 v74, v73, v85
	v_mul_f32_e32 v72, v83, v72
	v_sub_f32_e32 v74, v84, v74
	v_add_f32_e32 v74, v74, v72
	v_add_f32_e32 v76, v73, v74
	v_mul_f32_e32 v77, v76, v76
	v_fmamk_f32 v72, v77, 0x3e9b6dac, v205
	v_fmaak_f32 v173, v77, v72, 0x3f2aaada
	v_cvt_f32_i32_e32 v72, v80
	v_sub_f32_e32 v73, v76, v73
	v_sub_f32_e32 v73, v74, v73
	v_ldexp_f32 v78, v73, 1
	v_mul_f32_e32 v73, v76, v77
	v_ldexp_f32 v75, v76, 1
	v_pk_mul_f32 v[76:77], v[72:73], v[172:173]
	s_nop 0
	v_fma_f32 v74, v72, s15, -v76
	v_fmac_f32_e32 v74, 0xb102e308, v72
	v_pk_add_f32 v[72:73], v[76:77], v[74:75]
	s_nop 0
	v_sub_f32_e32 v75, v73, v75
	v_sub_f32_e32 v75, v77, v75
	v_add_f32_e32 v79, v78, v75
	v_mov_b32_e32 v78, v76
	v_pk_add_f32 v[76:77], v[72:73], v[76:77] neg_lo:[0,1] neg_hi:[0,1]
	v_pk_add_f32 v[80:81], v[72:73], v[78:79]
	v_mov_b32_e32 v75, v72
	v_mov_b32_e32 v77, v81
	v_pk_add_f32 v[82:83], v[74:75], v[76:77] neg_lo:[0,1] neg_hi:[0,1]
	v_pk_add_f32 v[74:75], v[74:75], v[76:77]
	v_mov_b32_e32 v78, v79
	v_pk_add_f32 v[76:77], v[74:75], v[72:73] op_sel:[1,0] op_sel_hi:[0,1] neg_lo:[0,1] neg_hi:[0,1]
	v_pk_add_f32 v[84:85], v[80:81], v[76:77] op_sel_hi:[1,0] neg_lo:[0,1] neg_hi:[0,1]
	v_mov_b32_e32 v80, v81
	v_mov_b32_e32 v81, v75
	v_pk_mov_b32 v[76:77], v[72:73], v[76:77] op_sel:[1,0]
	v_mov_b32_e32 v79, v72
	v_pk_add_f32 v[76:77], v[80:81], v[76:77] neg_lo:[0,1] neg_hi:[0,1]
	v_mov_b32_e32 v84, v82
	v_pk_add_f32 v[72:73], v[78:79], v[76:77] neg_lo:[0,1] neg_hi:[0,1]
	v_mov_b32_e32 v83, v75
	v_pk_add_f32 v[76:77], v[84:85], v[72:73]
	s_nop 0
	v_pk_add_f32 v[78:79], v[76:77], v[76:77] op_sel:[0,1] op_sel_hi:[1,0]
	s_nop 0
	v_pk_add_f32 v[74:75], v[74:75], v[78:79] op_sel:[1,0] op_sel_hi:[0,1]
	v_mov_b32_e32 v77, v74
	v_pk_add_f32 v[80:81], v[76:77], v[82:83] neg_lo:[0,1] neg_hi:[0,1]
	v_mov_b32_e32 v73, v78
	v_sub_f32_e32 v75, v76, v80
	v_pk_add_f32 v[72:73], v[72:73], v[80:81] neg_lo:[0,1] neg_hi:[0,1]
	v_sub_f32_e32 v75, v82, v75
	v_add_f32_e32 v72, v72, v75
	v_add_f32_e32 v72, v72, v73
	v_add_f32_e32 v72, v74, v72
	v_cndmask_b32_e32 v72, v208, v72, vcc
	v_cmp_lt_f32_e64 vcc, |v2|, s64
	s_nop 1
	v_cndmask_b32_e32 v2, v72, v2, vcc
